# attention: row sums by f32 VALU adds instead of ones-fragment MFMAs (4 fewer MFMAs per tile), transposed at the end
# baseline (speedup 1.0000x reference)
.LBB0_818:
	v_add_f32_e32 v230, v230, v252
	v_cmp_lt_i32_e32 vcc, v199, v193
	s_nop 1
	v_cndmask_b32_e32 v231, v191, v199, vcc
	v_lshlrev_b32_e32 v231, 2, v231
	ds_bpermute_b32 v231, v231, v230
	s_waitcnt lgkmcnt(0)
	v_add_f32_e32 v230, v230, v231
	s_and_saveexec_b64 s[2:3], s[10:11]
	ds_write_b32 v203, v230 offset:61440
	s_or_b64 exec, exec, s[2:3]
	s_waitcnt lgkmcnt(0)
	ds_read_b128 v[32:35], v204 offset:61440
	ds_read_b128 v[36:39], v204 offset:61472
	ds_read_b128 v[40:43], v204 offset:61504
	ds_read_b128 v[44:47], v204 offset:61536
	s_waitcnt lgkmcnt(0)
	s_nop 5
	v_div_scale_f32 v48, s[0:1], v32, v32, 1.0
	v_rcp_f32_e32 v49, v48
	v_lshl_add_u32 v50, v178, 12, s37
	v_lshlrev_b32_e32 v51, 1, v179
	s_mov_b64 s[2:3], 0
	v_fma_f32 v52, -v48, v49, 1.0
	v_fmac_f32_e32 v49, v52, v49
	v_div_scale_f32 v52, vcc, 1.0, v32, 1.0
	v_mul_f32_e32 v53, v52, v49
	v_fma_f32 v54, -v48, v53, v52
	v_fmac_f32_e32 v53, v54, v49
	v_fma_f32 v48, -v48, v53, v52
	v_div_fmas_f32 v48, v48, v49, v53
	v_div_fixup_f32 v32, v48, v32, 1.0
	v_mul_f32_e32 v0, v32, v0
	v_lshlrev_b32_e32 v48, 9, v171
	v_cvt_pk_bf16_f32 v0, v0, s0
	v_add3_u32 v48, v50, v51, v48
	ds_write_b16 v48, v0 offset:62464
	v_div_scale_f32 v0, s[0:1], v33, v33, 1.0
	v_rcp_f32_e32 v51, v0
	v_mul_f32_e32 v16, v16, v32
	v_cvt_pk_bf16_f32 v16, v16, s0
	ds_write_b16 v48, v16 offset:62528
	v_fma_f32 v16, -v0, v51, 1.0
	v_fmac_f32_e32 v51, v16, v51
	v_div_scale_f32 v16, vcc, 1.0, v33, 1.0
	v_mul_f32_e32 v32, v16, v51
	v_fma_f32 v52, -v0, v32, v16
	v_fmac_f32_e32 v32, v52, v51
	v_fma_f32 v0, -v0, v32, v16
	v_div_fmas_f32 v0, v0, v51, v32
	v_div_fixup_f32 v0, v0, v33, 1.0
	v_mul_f32_e32 v1, v0, v1
	v_cvt_pk_bf16_f32 v1, v1, s0
	ds_write_b16 v48, v1 offset:62592
	v_div_scale_f32 v1, s[0:1], v34, v34, 1.0
	v_rcp_f32_e32 v16, v1
	v_mul_f32_e32 v0, v17, v0
	v_cvt_pk_bf16_f32 v0, v0, s0
	ds_write_b16 v48, v0 offset:62656
	v_fma_f32 v0, -v1, v16, 1.0
	v_fmac_f32_e32 v16, v0, v16
	v_div_scale_f32 v0, vcc, 1.0, v34, 1.0
	v_mul_f32_e32 v17, v0, v16
	v_fma_f32 v32, -v1, v17, v0
	v_fmac_f32_e32 v17, v32, v16
	v_fma_f32 v0, -v1, v17, v0
	v_div_fmas_f32 v0, v0, v16, v17
	v_div_fixup_f32 v0, v0, v34, 1.0
	v_mul_f32_e32 v1, v0, v2
	v_cvt_pk_bf16_f32 v1, v1, s0
	ds_write_b16 v48, v1 offset:62720
	v_div_scale_f32 v1, s[0:1], v35, v35, 1.0
	v_rcp_f32_e32 v2, v1
	v_mul_f32_e32 v0, v18, v0
	v_cvt_pk_bf16_f32 v0, v0, s0
	ds_write_b16 v48, v0 offset:62784
	v_fma_f32 v0, -v1, v2, 1.0
	v_fmac_f32_e32 v2, v0, v2
	v_div_scale_f32 v0, vcc, 1.0, v35, 1.0
	v_mul_f32_e32 v16, v0, v2
	v_fma_f32 v17, -v1, v16, v0
	v_fmac_f32_e32 v16, v17, v2
	v_fma_f32 v0, -v1, v16, v0
	v_div_fmas_f32 v0, v0, v2, v16
	v_div_fixup_f32 v0, v0, v35, 1.0
	v_mul_f32_e32 v1, v0, v3
	v_cvt_pk_bf16_f32 v1, v1, s0
	ds_write_b16 v48, v1 offset:62848
	v_div_scale_f32 v1, s[0:1], v36, v36, 1.0
	v_rcp_f32_e32 v2, v1
	v_mul_f32_e32 v0, v19, v0
	v_cvt_pk_bf16_f32 v0, v0, s0
	ds_write_b16 v48, v0 offset:62912
	v_fma_f32 v0, -v1, v2, 1.0
	v_fmac_f32_e32 v2, v0, v2
	v_div_scale_f32 v0, vcc, 1.0, v36, 1.0
	v_mul_f32_e32 v3, v0, v2
	v_fma_f32 v16, -v1, v3, v0
	v_fmac_f32_e32 v3, v16, v2
	v_fma_f32 v0, -v1, v3, v0
	v_div_fmas_f32 v0, v0, v2, v3
	v_div_fixup_f32 v0, v0, v36, 1.0
	v_mul_f32_e32 v1, v0, v4
	v_cvt_pk_bf16_f32 v1, v1, s0
	ds_write_b16 v48, v1 offset:63488
	v_div_scale_f32 v1, s[0:1], v37, v37, 1.0
	v_rcp_f32_e32 v2, v1
	v_mul_f32_e32 v0, v20, v0
	v_cvt_pk_bf16_f32 v0, v0, s0
	ds_write_b16 v48, v0 offset:63552
	v_fma_f32 v0, -v1, v2, 1.0
	v_fmac_f32_e32 v2, v0, v2
	v_div_scale_f32 v0, vcc, 1.0, v37, 1.0
	v_mul_f32_e32 v3, v0, v2
	v_fma_f32 v4, -v1, v3, v0
	v_fmac_f32_e32 v3, v4, v2
	v_fma_f32 v0, -v1, v3, v0
	v_div_fmas_f32 v0, v0, v2, v3
	v_div_fixup_f32 v0, v0, v37, 1.0
	v_mul_f32_e32 v1, v0, v5
	v_cvt_pk_bf16_f32 v1, v1, s0
	ds_write_b16 v48, v1 offset:63616
	v_div_scale_f32 v1, s[0:1], v38, v38, 1.0
	v_rcp_f32_e32 v2, v1
	v_mul_f32_e32 v0, v21, v0
	v_cvt_pk_bf16_f32 v0, v0, s0
	ds_write_b16 v48, v0 offset:63680
	v_fma_f32 v0, -v1, v2, 1.0
	v_fmac_f32_e32 v2, v0, v2
	v_div_scale_f32 v0, vcc, 1.0, v38, 1.0
	v_mul_f32_e32 v3, v0, v2
	v_fma_f32 v4, -v1, v3, v0
	v_fmac_f32_e32 v3, v4, v2
	v_fma_f32 v0, -v1, v3, v0
	v_div_fmas_f32 v0, v0, v2, v3
	v_div_fixup_f32 v0, v0, v38, 1.0
	v_mul_f32_e32 v1, v0, v6
	v_cvt_pk_bf16_f32 v1, v1, s0
	ds_write_b16 v48, v1 offset:63744
	v_div_scale_f32 v1, s[0:1], v39, v39, 1.0
	v_rcp_f32_e32 v2, v1
	v_mul_f32_e32 v0, v22, v0
	v_cvt_pk_bf16_f32 v0, v0, s0
	ds_write_b16 v48, v0 offset:63808
	v_fma_f32 v0, -v1, v2, 1.0
	v_fmac_f32_e32 v2, v0, v2
	v_div_scale_f32 v0, vcc, 1.0, v39, 1.0
	v_mul_f32_e32 v3, v0, v2
	v_fma_f32 v4, -v1, v3, v0
	v_fmac_f32_e32 v3, v4, v2
	v_fma_f32 v0, -v1, v3, v0
	v_div_fmas_f32 v0, v0, v2, v3
	v_div_fixup_f32 v0, v0, v39, 1.0
	v_mul_f32_e32 v1, v0, v7
	v_cvt_pk_bf16_f32 v1, v1, s0
	ds_write_b16 v48, v1 offset:63872
	v_div_scale_f32 v1, s[0:1], v40, v40, 1.0
	v_rcp_f32_e32 v2, v1
	v_mul_f32_e32 v0, v23, v0
	v_cvt_pk_bf16_f32 v0, v0, s0
	ds_write_b16 v48, v0 offset:63936
	v_fma_f32 v0, -v1, v2, 1.0
	v_fmac_f32_e32 v2, v0, v2
	v_div_scale_f32 v0, vcc, 1.0, v40, 1.0
	v_mul_f32_e32 v3, v0, v2
	v_fma_f32 v4, -v1, v3, v0
	v_fmac_f32_e32 v3, v4, v2
	v_fma_f32 v0, -v1, v3, v0
	v_div_fmas_f32 v0, v0, v2, v3
	v_div_fixup_f32 v0, v0, v40, 1.0
	v_mul_f32_e32 v1, v0, v8
	v_cvt_pk_bf16_f32 v1, v1, s0
	ds_write_b16 v48, v1 offset:64512
	v_div_scale_f32 v1, s[0:1], v41, v41, 1.0
	v_rcp_f32_e32 v2, v1
	v_mul_f32_e32 v0, v24, v0
	v_cvt_pk_bf16_f32 v0, v0, s0
	ds_write_b16 v48, v0 offset:64576
	v_fma_f32 v0, -v1, v2, 1.0
	v_fmac_f32_e32 v2, v0, v2
	v_div_scale_f32 v0, vcc, 1.0, v41, 1.0
	v_mul_f32_e32 v3, v0, v2
	v_fma_f32 v4, -v1, v3, v0
	v_fmac_f32_e32 v3, v4, v2
	v_fma_f32 v0, -v1, v3, v0
	v_div_fmas_f32 v0, v0, v2, v3
	v_div_fixup_f32 v0, v0, v41, 1.0
	v_mul_f32_e32 v1, v0, v9
	v_cvt_pk_bf16_f32 v1, v1, s0
	ds_write_b16 v48, v1 offset:64640
	v_div_scale_f32 v1, s[0:1], v42, v42, 1.0
	v_rcp_f32_e32 v2, v1
	v_mul_f32_e32 v0, v25, v0
	v_cvt_pk_bf16_f32 v0, v0, s0
	ds_write_b16 v48, v0 offset:64704
	v_fma_f32 v0, -v1, v2, 1.0
	v_fmac_f32_e32 v2, v0, v2
	v_div_scale_f32 v0, vcc, 1.0, v42, 1.0
	v_mul_f32_e32 v3, v0, v2
	v_fma_f32 v4, -v1, v3, v0
	v_fmac_f32_e32 v3, v4, v2
	v_fma_f32 v0, -v1, v3, v0
	v_div_fmas_f32 v0, v0, v2, v3
	v_div_fixup_f32 v0, v0, v42, 1.0
	v_mul_f32_e32 v1, v0, v10
	v_cvt_pk_bf16_f32 v1, v1, s0
	ds_write_b16 v48, v1 offset:64768
	v_div_scale_f32 v1, s[0:1], v43, v43, 1.0
	v_rcp_f32_e32 v2, v1
	v_mul_f32_e32 v0, v26, v0
	v_cvt_pk_bf16_f32 v0, v0, s0
	ds_write_b16 v48, v0 offset:64832
	v_fma_f32 v0, -v1, v2, 1.0
	v_fmac_f32_e32 v2, v0, v2
	v_div_scale_f32 v0, vcc, 1.0, v43, 1.0
	v_mul_f32_e32 v3, v0, v2
	v_fma_f32 v4, -v1, v3, v0
	v_fmac_f32_e32 v3, v4, v2
	v_fma_f32 v0, -v1, v3, v0
	v_div_fmas_f32 v0, v0, v2, v3
	v_div_fixup_f32 v0, v0, v43, 1.0
	v_mul_f32_e32 v1, v0, v11
	v_cvt_pk_bf16_f32 v1, v1, s0
	ds_write_b16 v48, v1 offset:64896
	v_div_scale_f32 v1, s[0:1], v44, v44, 1.0
	v_rcp_f32_e32 v2, v1
	v_mul_f32_e32 v0, v27, v0
	v_cvt_pk_bf16_f32 v0, v0, s0
	ds_write_b16 v48, v0 offset:64960
	v_fma_f32 v0, -v1, v2, 1.0
	v_fmac_f32_e32 v2, v0, v2
	v_div_scale_f32 v0, vcc, 1.0, v44, 1.0
	v_mul_f32_e32 v3, v0, v2
	v_fma_f32 v4, -v1, v3, v0
	v_fmac_f32_e32 v3, v4, v2
	v_fma_f32 v0, -v1, v3, v0
	v_div_fmas_f32 v0, v0, v2, v3
	v_div_fixup_f32 v0, v0, v44, 1.0
	v_mul_f32_e32 v1, v0, v12
	v_add_u32_e32 v49, 0xf400, v48
	v_cvt_pk_bf16_f32 v1, v1, s0
	ds_write_b16 v49, v1 offset:3072
	v_div_scale_f32 v1, s[0:1], v45, v45, 1.0
	v_rcp_f32_e32 v2, v1
	v_mul_f32_e32 v0, v28, v0
	v_cvt_pk_bf16_f32 v0, v0, s0
	ds_write_b16 v49, v0 offset:3136
	v_fma_f32 v0, -v1, v2, 1.0
	v_fmac_f32_e32 v2, v0, v2
	v_div_scale_f32 v0, vcc, 1.0, v45, 1.0
	v_mul_f32_e32 v3, v0, v2
	v_fma_f32 v4, -v1, v3, v0
	v_fmac_f32_e32 v3, v4, v2
	v_fma_f32 v0, -v1, v3, v0
	v_div_fmas_f32 v0, v0, v2, v3
	v_div_fixup_f32 v0, v0, v45, 1.0
	v_mul_f32_e32 v1, v0, v13
	v_cvt_pk_bf16_f32 v1, v1, s0
	ds_write_b16 v49, v1 offset:3200
	v_div_scale_f32 v1, s[0:1], v46, v46, 1.0
	v_rcp_f32_e32 v2, v1
	v_mul_f32_e32 v0, v29, v0
	v_cvt_pk_bf16_f32 v0, v0, s0
	ds_write_b16 v49, v0 offset:3264
	v_fma_f32 v0, -v1, v2, 1.0
	v_fmac_f32_e32 v2, v0, v2
	v_div_scale_f32 v0, vcc, 1.0, v46, 1.0
	v_mul_f32_e32 v3, v0, v2
	v_fma_f32 v4, -v1, v3, v0
	v_fmac_f32_e32 v3, v4, v2
	v_fma_f32 v0, -v1, v3, v0
	v_div_fmas_f32 v0, v0, v2, v3
	v_div_fixup_f32 v0, v0, v46, 1.0
	v_mul_f32_e32 v1, v0, v14
	v_cvt_pk_bf16_f32 v1, v1, s0
	ds_write_b16 v49, v1 offset:3328
	v_div_scale_f32 v1, s[0:1], v47, v47, 1.0
	v_rcp_f32_e32 v2, v1
	v_mul_f32_e32 v0, v30, v0
	v_cvt_pk_bf16_f32 v0, v0, s0
	ds_write_b16 v49, v0 offset:3392
	v_fma_f32 v0, -v1, v2, 1.0
	v_fmac_f32_e32 v2, v0, v2
	v_div_scale_f32 v0, vcc, 1.0, v47, 1.0
	v_mul_f32_e32 v3, v0, v2
	v_fma_f32 v4, -v1, v3, v0
	v_fmac_f32_e32 v3, v4, v2
	v_fma_f32 v0, -v1, v3, v0
	v_div_fmas_f32 v0, v0, v2, v3
	v_div_fixup_f32 v0, v0, v47, 1.0
	v_mul_f32_e32 v1, v0, v15
	v_mul_f32_e32 v0, v31, v0
	s_ashr_i32 s1, s41, 31
	v_cvt_pk_bf16_f32 v1, v1, s0
	v_cvt_pk_bf16_f32 v0, v0, s0
	s_add_u32 s0, s41, s39
	s_addc_u32 s1, s1, 0
	v_ashrrev_i32_e32 v171, 31, v170
	ds_write_b16 v49, v1 offset:3456
	ds_write_b16 v49, v0 offset:3520
	v_lshl_add_u64 v[0:1], s[0:1], 0, v[170:171]
	v_lshlrev_b64 v[0:1], 10, v[0:1]
	s_lshl_b32 s0, s52, 7
	v_lshlrev_b32_e32 v2, 1, v168
	v_lshl_add_u64 v[0:1], s[58:59], 0, v[0:1]
	s_and_b32 s52, s0, 0x380
	v_and_b32_e32 v168, 0x70, v2
	v_lshl_add_u64 v[0:1], v[0:1], 0, s[52:53]
	v_lshrrev_b32_e32 v12, 3, v173
	v_add_u32_e32 v13, v50, v168
	s_waitcnt lgkmcnt(0)
	v_lshl_add_u64 v[8:9], v[0:1], 0, v[168:169]
	v_lshl_add_u32 v0, v12, 7, v13
	v_or_b32_e32 v14, 8, v12
	ds_read_b128 v[0:3], v0 offset:62464
	v_lshl_add_u32 v4, v14, 7, v13
	ds_read_b128 v[4:7], v4 offset:62464
	v_lshlrev_b32_e32 v168, 10, v12
	v_lshl_add_u64 v[10:11], v[8:9], 0, v[168:169]
	v_lshlrev_b32_e32 v168, 10, v14
	s_waitcnt lgkmcnt(1)
	global_store_dwordx4 v[10:11], v[0:3], off
	s_nop 1
	v_lshl_add_u64 v[0:1], v[8:9], 0, v[168:169]
	s_waitcnt lgkmcnt(0)
	global_store_dwordx4 v[0:1], v[4:7], off
	s_nop 1
	v_or_b32_e32 v4, 16, v12
	v_lshl_add_u32 v0, v4, 7, v13
	v_or_b32_e32 v12, 24, v12
	ds_read_b128 v[0:3], v0 offset:62464
	v_lshlrev_b32_e32 v168, 10, v4
	v_lshl_add_u32 v4, v12, 7, v13
	ds_read_b128 v[4:7], v4 offset:62464
	v_lshl_add_u64 v[10:11], v[8:9], 0, v[168:169]
	v_lshlrev_b32_e32 v168, 10, v12
	s_waitcnt lgkmcnt(1)
	global_store_dwordx4 v[10:11], v[0:3], off
	s_nop 1
	v_lshl_add_u64 v[0:1], v[8:9], 0, v[168:169]
	s_waitcnt lgkmcnt(0)
	global_store_dwordx4 v[0:1], v[4:7], off

.LBB0_829:
	s_or_b64 exec, exec, s[8:9]
	s_lshl_b32 s0, s0, 1
	s_add_i32 s63, s0, 4
	s_lshl_b32 s72, s1, 1
	v_and_b32_e32 v0, 0x3fffffc0, v2
	s_mov_b64 s[8:9], 0x2000
	s_cmp_lg_u32 s10, -1
	v_lshl_add_u32 v19, v0, 2, s37
	v_lshl_add_u64 v[0:1], v[20:21], 0, s[8:9]
	v_readfirstlane_b32 s1, v3
	s_cselect_b32 s8, s10, 0
	s_add_i32 s1, s8, s1
	s_addk_i32 s1, 0x2000
	s_mov_b32 s8, m0
	s_mov_b32 m0, s1
	s_nop 0
	global_load_lds_dwordx4 v[0:1], off
	s_mov_b32 m0, s8
	v_lshlrev_b32_e32 v0, 1, v2
	v_and_b32_e32 v30, 32, v0
	v_lshlrev_b32_e32 v182, 2, v171
	v_lshrrev_b32_e32 v0, 2, v2
	v_and_or_b32 v0, v0, 3, v182
	v_lshlrev_b32_e32 v32, 6, v0
	v_lshlrev_b32_e32 v0, 4, v179
	v_lshlrev_b32_e32 v1, 10, v171
	s_waitcnt vmcnt(0)
	s_barrier
	v_add3_u32 v183, 16, v0, v1
	ds_read_b128 v[22:25], v183
	ds_read_b128 v[26:29], v183 offset:512
	s_waitcnt vmcnt(5) lgkmcnt(1)
	v_mfma_f32_32x32x16_bf16 v[48:63], v[22:25], v[128:131], 0
	s_mov_b32 s8, s53
	s_mov_b32 s9, s53
	v_lshl_add_u32 v203, v179, 2, v19
	v_lshl_add_u32 v204, v171, 4, v19
	v_mov_b32_e32 v19, v169
	v_lshlrev_b32_e32 v168, 3, v2
	s_mov_b32 s10, s53
	s_waitcnt lgkmcnt(0)
	v_mfma_f32_32x32x16_bf16 v[64:79], v[26:29], v[128:131], 0
	ds_read_b128 v[22:25], v183 offset:2048
	ds_read_b128 v[26:29], v183 offset:2560
	s_mov_b32 s11, s53
	s_mov_b32 s12, s53
	s_mov_b32 s13, s53
	s_mov_b32 s14, s53
	s_mov_b32 s15, s53
	s_mov_b32 s16, s53
	s_waitcnt vmcnt(4) lgkmcnt(1)
	v_mfma_f32_32x32x16_bf16 v[48:63], v[22:25], v[132:135], v[48:63]
	s_mov_b32 s17, s53
	s_mov_b32 s18, s53
	s_mov_b32 s19, s53
	s_mov_b32 s20, s53
	s_mov_b32 s21, s53
	s_mov_b32 s22, s53
	s_mov_b32 s23, s53
	s_waitcnt lgkmcnt(0)
	v_mfma_f32_32x32x16_bf16 v[64:79], v[26:29], v[132:135], v[64:79]
	ds_read_b128 v[22:25], v183 offset:4096
	ds_read_b128 v[26:29], v183 offset:4608
	v_mov_b64_e32 v[0:1], s[8:9]
	v_lshl_add_u64 v[18:19], s[2:3], 0, v[18:19]
	v_and_b32_e32 v31, 24, v168
	v_mov_b64_e32 v[14:15], s[22:23]
	v_lshl_add_u64 v[16:17], v[16:17], 1, v[18:19]
	v_mov_b64_e32 v[2:3], s[10:11]
	s_waitcnt vmcnt(3) lgkmcnt(1)
	v_mfma_f32_32x32x16_bf16 v[48:63], v[22:25], v[136:139], v[48:63]
	v_mov_b64_e32 v[4:5], s[12:13]
	v_mov_b64_e32 v[6:7], s[14:15]
	v_mov_b64_e32 v[8:9], s[16:17]
	v_mov_b64_e32 v[10:11], s[18:19]
	v_mov_b64_e32 v[12:13], s[20:21]
	v_lshl_add_u64 v[174:175], v[20:21], 0, s[56:57]
	v_lshl_add_u64 v[176:177], s[60:61], 0, v[16:17]
	s_waitcnt lgkmcnt(0)
	v_mfma_f32_32x32x16_bf16 v[64:79], v[26:29], v[136:139], v[64:79]
	ds_read_b128 v[22:25], v183 offset:6144
	ds_read_b128 v[26:29], v183 offset:6656
	v_mov_b64_e32 v[94:95], v[14:15]
	s_mov_b32 s62, 1
	s_mov_b32 s68, 2
	s_mov_b32 s73, 0
	v_cmp_lt_i32_e64 s[8:9], 1, v178
	v_cmp_gt_u32_e64 s[10:11], 32, v173
	s_waitcnt vmcnt(2) lgkmcnt(1)
	v_mfma_f32_32x32x16_bf16 v[48:63], v[22:25], v[140:143], v[48:63]
	s_add_i32 s18, s40, s0
	s_mov_b32 s0, 0
	v_mov_b64_e32 v[92:93], v[12:13]
	v_mov_b64_e32 v[90:91], v[10:11]
	v_mov_b64_e32 v[88:89], v[8:9]
	v_mov_b64_e32 v[86:87], v[6:7]
	v_mov_b64_e32 v[84:85], v[4:5]
	s_waitcnt lgkmcnt(0)
	v_mfma_f32_32x32x16_bf16 v[64:79], v[26:29], v[140:143], v[64:79]
	ds_read_b128 v[22:25], v183 offset:8192
	ds_read_b128 v[26:29], v183 offset:8704
	v_mov_b64_e32 v[82:83], v[2:3]
	v_mov_b64_e32 v[80:81], v[0:1]
	s_mov_b32 s1, 0
	s_waitcnt vmcnt(1) lgkmcnt(1)
	v_mfma_f32_32x32x16_bf16 v[48:63], v[22:25], v[144:147], v[48:63]
	s_waitcnt lgkmcnt(0)
	v_mfma_f32_32x32x16_bf16 v[64:79], v[26:29], v[144:147], v[64:79]
	ds_read_b128 v[22:25], v183 offset:10240
	ds_read_b128 v[26:29], v183 offset:10752
	s_waitcnt vmcnt(0) lgkmcnt(1)
	v_mfma_f32_32x32x16_bf16 v[48:63], v[22:25], v[148:151], v[48:63]
	v_add_u32_e32 v22, 16, v30
	v_add3_u32 v202, v22, v31, v32
	v_mov_b64_e32 v[46:47], v[14:15]
	v_mov_b64_e32 v[44:45], v[12:13]
	v_mov_b64_e32 v[42:43], v[10:11]
	v_mov_b64_e32 v[40:41], v[8:9]
	v_mov_b64_e32 v[38:39], v[6:7]
	s_waitcnt lgkmcnt(0)
	v_mfma_f32_32x32x16_bf16 v[64:79], v[26:29], v[148:151], v[64:79]
	v_mov_b64_e32 v[30:31], v[14:15]
	v_mov_b64_e32 v[28:29], v[12:13]
	v_mov_b64_e32 v[26:27], v[10:11]
	v_mov_b64_e32 v[24:25], v[8:9]
	v_mov_b64_e32 v[22:23], v[6:7]
	v_mov_b64_e32 v[20:21], v[4:5]
	v_mov_b64_e32 v[18:19], v[2:3]
	v_mov_b64_e32 v[16:17], v[0:1]
	v_mov_b64_e32 v[36:37], v[4:5]
	v_mov_b64_e32 v[34:35], v[2:3]
	v_mov_b64_e32 v[32:33], v[0:1]
	v_mov_b32_e32 v230, 0
	v_mov_b32_e32 v252, 0

.LBB0_850:
	v_exp_f32_e64 v231, -v205
	s_and_saveexec_b64 s[16:17], s[10:11]
	v_exp_f32_e64 v81, -v205
	ds_write_b32 v203, v81 offset:61440
	s_or_b64 exec, exec, s[16:17]
	v_mul_f32_e32 v230, v230, v231
	v_mul_f32_e32 v252, v252, v231
	s_waitcnt lgkmcnt(0)
	ds_read_b128 v[152:155], v204 offset:61440
	ds_read_b128 v[156:159], v204 offset:61472
	ds_read_b128 v[160:163], v204 offset:61504
	ds_read_b128 v[164:167], v204 offset:61536
	s_and_saveexec_b64 s[16:17], s[2:3]
	s_cbranch_execz .LBB0_854
	v_sub_f32_e32 v111, v111, v205
	v_sub_f32_e32 v110, v110, v205
	v_sub_f32_e32 v109, v109, v205
	v_sub_f32_e32 v108, v108, v205
	v_sub_f32_e32 v107, v107, v205
	v_sub_f32_e32 v106, v106, v205
	v_sub_f32_e32 v105, v105, v205
	v_sub_f32_e32 v104, v104, v205
	v_sub_f32_e32 v103, v103, v205
	v_sub_f32_e32 v102, v102, v205
	v_sub_f32_e32 v101, v101, v205
	v_sub_f32_e32 v100, v100, v205
	v_sub_f32_e32 v99, v99, v205
	v_sub_f32_e32 v98, v98, v205
	v_sub_f32_e32 v97, v97, v205
	v_sub_f32_e32 v96, v96, v205
	v_sub_f32_e32 v127, v127, v205
	v_sub_f32_e32 v126, v126, v205
	v_sub_f32_e32 v125, v125, v205
	v_sub_f32_e32 v124, v124, v205
	v_sub_f32_e32 v123, v123, v205
	v_sub_f32_e32 v122, v122, v205
	v_sub_f32_e32 v121, v121, v205
	v_sub_f32_e32 v120, v120, v205
	v_sub_f32_e32 v119, v119, v205
	v_sub_f32_e32 v118, v118, v205
	v_sub_f32_e32 v117, v117, v205
	v_sub_f32_e32 v116, v116, v205
	v_sub_f32_e32 v115, v115, v205
	v_sub_f32_e32 v114, v114, v205
	v_sub_f32_e32 v113, v113, v205
	v_sub_f32_e32 v112, v112, v205

.LBB0_855:
	v_exp_f32_e32 v48, v48
	v_exp_f32_e32 v49, v49
	v_exp_f32_e32 v50, v50
	v_exp_f32_e32 v51, v51
	v_exp_f32_e32 v52, v52
	v_exp_f32_e32 v53, v53
	v_exp_f32_e32 v54, v54
	v_exp_f32_e32 v55, v55
	v_lshl_add_u32 v205, s62, 13, v202
	v_cvt_pk_bf16_f32 v152, v48, v49
	v_add_f32_e32 v230, v230, v48
	v_add_f32_e32 v252, v252, v49
	v_cvt_pk_bf16_f32 v153, v50, v51
	v_add_f32_e32 v230, v230, v50
	v_add_f32_e32 v252, v252, v51
	v_cvt_pk_bf16_f32 v154, v52, v53
	v_add_f32_e32 v230, v230, v52
	v_add_f32_e32 v252, v252, v53
	v_cvt_pk_bf16_f32 v155, v54, v55
	v_add_f32_e32 v230, v230, v54
	v_add_f32_e32 v252, v252, v55
	ds_read_b64_tr_b16 v[156:157], v205 offset:36864
	ds_read_b64_tr_b16 v[158:159], v205 offset:37376
	v_exp_f32_e32 v56, v56
	v_exp_f32_e32 v57, v57
	v_exp_f32_e32 v58, v58
	s_waitcnt lgkmcnt(0)
	v_mfma_f32_32x32x16_bf16 v[0:15], v[152:155], v[156:159], v[0:15]
	ds_read_b64_tr_b16 v[156:157], v205 offset:37888
	ds_read_b64_tr_b16 v[160:161], v205 offset:40960
	ds_read_b64_tr_b16 v[162:163], v205 offset:41472
	ds_read_b64_tr_b16 v[158:159], v205 offset:38400
	v_exp_f32_e32 v59, v59
	v_exp_f32_e32 v60, v60
	v_exp_f32_e32 v61, v61
	v_exp_f32_e32 v62, v62
	v_exp_f32_e32 v63, v63
	s_mov_b32 s46, s44
	s_mov_b32 s47, s44
	s_mov_b32 s45, s44
	v_mov_b64_e32 v[166:167], s[46:47]
	v_mov_b64_e32 v[164:165], s[44:45]
	s_waitcnt lgkmcnt(1)
	v_mfma_f32_32x32x16_bf16 v[16:31], v[152:155], v[160:163], v[16:31]
	v_cvt_pk_bf16_f32 v160, v56, v57
	v_add_f32_e32 v230, v230, v56
	v_add_f32_e32 v252, v252, v57
	v_cvt_pk_bf16_f32 v161, v58, v59
	v_add_f32_e32 v230, v230, v58
	v_add_f32_e32 v252, v252, v59
	v_cvt_pk_bf16_f32 v162, v60, v61
	v_add_f32_e32 v230, v230, v60
	v_add_f32_e32 v252, v252, v61
	v_cvt_pk_bf16_f32 v163, v62, v63
	v_add_f32_e32 v230, v230, v62
	v_add_f32_e32 v252, v252, v63
	v_exp_f32_e32 v64, v64
	v_exp_f32_e32 v65, v65
	v_exp_f32_e32 v66, v66
	ds_read_b64_tr_b16 v[152:153], v205 offset:41984
	ds_read_b64_tr_b16 v[154:155], v205 offset:42496
	v_exp_f32_e32 v67, v67
	v_exp_f32_e32 v68, v68
	v_exp_f32_e32 v69, v69
	v_exp_f32_e32 v70, v70
	v_exp_f32_e32 v71, v71
	v_exp_f32_e32 v72, v72
	s_waitcnt lgkmcnt(2)
	v_mfma_f32_32x32x16_bf16 v[0:15], v[160:163], v[156:159], v[0:15]
	ds_read_b64_tr_b16 v[156:157], v205 offset:38912
	ds_read_b64_tr_b16 v[158:159], v205 offset:39424
	v_exp_f32_e32 v73, v73
	v_exp_f32_e32 v74, v74
	v_exp_f32_e32 v75, v75
	v_exp_f32_e32 v76, v76
	v_exp_f32_e32 v77, v77
	v_exp_f32_e32 v78, v78
	s_waitcnt lgkmcnt(2)
	v_mfma_f32_32x32x16_bf16 v[16:31], v[160:163], v[152:155], v[16:31]
	v_cvt_pk_bf16_f32 v152, v64, v65
	v_add_f32_e32 v230, v230, v64
	v_add_f32_e32 v252, v252, v65
	v_cvt_pk_bf16_f32 v153, v66, v67
	v_add_f32_e32 v230, v230, v66
	v_add_f32_e32 v252, v252, v67
	v_cvt_pk_bf16_f32 v154, v68, v69
	v_add_f32_e32 v230, v230, v68
	v_add_f32_e32 v252, v252, v69
	v_cvt_pk_bf16_f32 v155, v70, v71
	v_add_f32_e32 v230, v230, v70
	v_add_f32_e32 v252, v252, v71
	v_exp_f32_e32 v79, v79
	s_waitcnt lgkmcnt(0)
	v_mfma_f32_32x32x16_bf16 v[0:15], v[152:155], v[156:159], v[0:15]
	ds_read_b64_tr_b16 v[156:157], v205 offset:43008
	ds_read_b64_tr_b16 v[158:159], v205 offset:43520
	ds_read_b64_tr_b16 v[160:161], v205 offset:39936
	ds_read_b64_tr_b16 v[162:163], v205 offset:40448
	s_waitcnt lgkmcnt(2)
	v_mfma_f32_32x32x16_bf16 v[16:31], v[152:155], v[156:159], v[16:31]
	v_cvt_pk_bf16_f32 v156, v72, v73
	v_add_f32_e32 v230, v230, v72
	v_add_f32_e32 v252, v252, v73
	v_cvt_pk_bf16_f32 v157, v74, v75
	v_add_f32_e32 v230, v230, v74
	v_add_f32_e32 v252, v252, v75
	v_cvt_pk_bf16_f32 v158, v76, v77
	v_add_f32_e32 v230, v230, v76
	v_add_f32_e32 v252, v252, v77
	v_cvt_pk_bf16_f32 v159, v78, v79
	v_add_f32_e32 v230, v230, v78
	v_add_f32_e32 v252, v252, v79
	ds_read_b64_tr_b16 v[152:153], v205 offset:44032
	ds_read_b64_tr_b16 v[154:155], v205 offset:44544
	s_waitcnt lgkmcnt(2)
	v_mfma_f32_32x32x16_bf16 v[0:15], v[156:159], v[160:163], v[0:15]
	s_waitcnt lgkmcnt(0)
	v_mfma_f32_32x32x16_bf16 v[16:31], v[156:159], v[152:155], v[16:31]
	s_andn2_b64 vcc, exec, s[14:15]
	s_cbranch_vccnz .LBB0_839

.LBB0_863:
	v_max_f32_e32 v152, v97, v97
	v_max_f32_e32 v153, v96, v96
	v_max_f32_e32 v152, v153, v152
	v_max3_f32 v153, v98, v99, v113
	v_max3_f32 v152, v152, v112, v114
	v_max3_f32 v152, v152, v115, v100
	v_max3_f32 v153, v153, v102, v103
	v_max3_f32 v152, v152, v101, v116
	v_max3_f32 v153, v153, v118, v119
	v_max3_f32 v152, v152, v117, v104
	v_max3_f32 v153, v153, v106, v107
	v_max3_f32 v152, v152, v105, v120
	v_max3_f32 v153, v153, v122, v123
	v_max3_f32 v152, v152, v121, v108
	v_max3_f32 v153, v153, v110, v111
	v_max3_f32 v152, v152, v109, v124
	v_max3_f32 v153, v153, v126, v127
	v_cmp_lt_i32_e32 vcc, v199, v193
	v_max3_f32 v152, v152, v125, v153
	s_nop 0
	v_cndmask_b32_e32 v153, v191, v199, vcc
	v_lshlrev_b32_e32 v153, 2, v153
	ds_bpermute_b32 v153, v153, v152
	s_waitcnt lgkmcnt(0)
	v_max_f32_e32 v153, v153, v153
	v_max_f32_e32 v152, v152, v153
	v_cmp_lt_f32_e32 vcc, s90, v152
	s_cbranch_vccz .LBB0_869
	v_max_f32_e32 v81, v152, v152
	v_max_f32_e32 v81, 0, v81
	v_exp_f32_e64 v231, -v81
	s_and_saveexec_b64 s[2:3], s[10:11]
	v_exp_f32_e64 v82, -v81
	ds_write_b32 v203, v82 offset:61440
	s_or_b64 exec, exec, s[2:3]
	v_mul_f32_e32 v230, v230, v231
	v_mul_f32_e32 v252, v252, v231
	s_waitcnt lgkmcnt(0)
	ds_read_b128 v[152:155], v204 offset:61440
	ds_read_b128 v[156:159], v204 offset:61472
	ds_read_b128 v[160:163], v204 offset:61504
	ds_read_b128 v[164:167], v204 offset:61536
	s_andn2_b64 vcc, exec, s[16:17]
	s_cbranch_vccnz .LBB0_868
	v_sub_f32_e32 v63, v63, v81
	v_sub_f32_e32 v62, v62, v81
	v_sub_f32_e32 v61, v61, v81
	v_sub_f32_e32 v60, v60, v81
	v_sub_f32_e32 v59, v59, v81
	v_sub_f32_e32 v58, v58, v81
	v_sub_f32_e32 v57, v57, v81
	v_sub_f32_e32 v56, v56, v81
	v_sub_f32_e32 v55, v55, v81
	v_sub_f32_e32 v54, v54, v81
	v_sub_f32_e32 v53, v53, v81
	v_sub_f32_e32 v52, v52, v81
	v_sub_f32_e32 v51, v51, v81
	v_sub_f32_e32 v50, v50, v81
	v_sub_f32_e32 v49, v49, v81
	v_sub_f32_e32 v48, v48, v81
	v_sub_f32_e32 v79, v79, v81
	v_sub_f32_e32 v78, v78, v81
	v_sub_f32_e32 v77, v77, v81
	v_sub_f32_e32 v76, v76, v81
	v_sub_f32_e32 v75, v75, v81
	v_sub_f32_e32 v74, v74, v81
	v_sub_f32_e32 v73, v73, v81
	v_sub_f32_e32 v72, v72, v81
	v_sub_f32_e32 v71, v71, v81
	v_sub_f32_e32 v70, v70, v81
	v_sub_f32_e32 v69, v69, v81
	v_sub_f32_e32 v68, v68, v81
	v_sub_f32_e32 v67, v67, v81
	v_sub_f32_e32 v66, v66, v81
	v_sub_f32_e32 v65, v65, v81
	v_sub_f32_e32 v64, v64, v81

.LBB0_869:
	v_exp_f32_e32 v96, v96
	v_exp_f32_e32 v97, v97
	v_exp_f32_e32 v98, v98
	v_exp_f32_e32 v99, v99
	v_exp_f32_e32 v100, v100
	v_exp_f32_e32 v101, v101
	v_exp_f32_e32 v102, v102
	v_exp_f32_e32 v103, v103
	v_lshl_add_u32 v205, s19, 13, v202
	v_cvt_pk_bf16_f32 v152, v96, v97
	v_add_f32_e32 v230, v230, v96
	v_add_f32_e32 v252, v252, v97
	v_cvt_pk_bf16_f32 v153, v98, v99
	v_add_f32_e32 v230, v230, v98
	v_add_f32_e32 v252, v252, v99
	v_cvt_pk_bf16_f32 v154, v100, v101
	v_add_f32_e32 v230, v230, v100
	v_add_f32_e32 v252, v252, v101
	v_cvt_pk_bf16_f32 v155, v102, v103
	v_add_f32_e32 v230, v230, v102
	v_add_f32_e32 v252, v252, v103
	ds_read_b64_tr_b16 v[156:157], v205 offset:36864
	ds_read_b64_tr_b16 v[158:159], v205 offset:37376
	v_exp_f32_e32 v104, v104
	v_exp_f32_e32 v105, v105
	v_exp_f32_e32 v106, v106
	s_waitcnt lgkmcnt(0)
	v_mfma_f32_32x32x16_bf16 v[0:15], v[152:155], v[156:159], v[0:15]
	ds_read_b64_tr_b16 v[156:157], v205 offset:37888
	ds_read_b64_tr_b16 v[160:161], v205 offset:40960
	ds_read_b64_tr_b16 v[162:163], v205 offset:41472
	ds_read_b64_tr_b16 v[158:159], v205 offset:38400
	v_exp_f32_e32 v107, v107
	v_exp_f32_e32 v108, v108
	v_exp_f32_e32 v109, v109
	v_exp_f32_e32 v110, v110
	v_exp_f32_e32 v111, v111
	s_mov_b32 s46, s44
	s_mov_b32 s47, s44
	s_mov_b32 s45, s44
	v_mov_b64_e32 v[166:167], s[46:47]
	v_mov_b64_e32 v[164:165], s[44:45]
	s_waitcnt lgkmcnt(1)
	v_mfma_f32_32x32x16_bf16 v[16:31], v[152:155], v[160:163], v[16:31]
	v_cvt_pk_bf16_f32 v160, v104, v105
	v_add_f32_e32 v230, v230, v104
	v_add_f32_e32 v252, v252, v105
	v_cvt_pk_bf16_f32 v161, v106, v107
	v_add_f32_e32 v230, v230, v106
	v_add_f32_e32 v252, v252, v107
	v_cvt_pk_bf16_f32 v162, v108, v109
	v_add_f32_e32 v230, v230, v108
	v_add_f32_e32 v252, v252, v109
	v_cvt_pk_bf16_f32 v163, v110, v111
	v_add_f32_e32 v230, v230, v110
	v_add_f32_e32 v252, v252, v111
	v_exp_f32_e32 v112, v112
	v_exp_f32_e32 v113, v113
	v_exp_f32_e32 v114, v114
	ds_read_b64_tr_b16 v[152:153], v205 offset:41984
	ds_read_b64_tr_b16 v[154:155], v205 offset:42496
	v_exp_f32_e32 v115, v115
	v_exp_f32_e32 v116, v116
	v_exp_f32_e32 v117, v117
	v_exp_f32_e32 v118, v118
	v_exp_f32_e32 v119, v119
	v_exp_f32_e32 v120, v120
	s_waitcnt lgkmcnt(2)
	v_mfma_f32_32x32x16_bf16 v[0:15], v[160:163], v[156:159], v[0:15]
	ds_read_b64_tr_b16 v[156:157], v205 offset:38912
	ds_read_b64_tr_b16 v[158:159], v205 offset:39424
	v_exp_f32_e32 v121, v121
	v_exp_f32_e32 v122, v122
	v_exp_f32_e32 v123, v123
	v_exp_f32_e32 v124, v124
	v_exp_f32_e32 v125, v125
	v_exp_f32_e32 v126, v126
	s_waitcnt lgkmcnt(2)
	v_mfma_f32_32x32x16_bf16 v[16:31], v[160:163], v[152:155], v[16:31]
	v_cvt_pk_bf16_f32 v152, v112, v113
	v_add_f32_e32 v230, v230, v112
	v_add_f32_e32 v252, v252, v113
	v_cvt_pk_bf16_f32 v153, v114, v115
	v_add_f32_e32 v230, v230, v114
	v_add_f32_e32 v252, v252, v115
	v_cvt_pk_bf16_f32 v154, v116, v117
	v_add_f32_e32 v230, v230, v116
	v_add_f32_e32 v252, v252, v117
	v_cvt_pk_bf16_f32 v155, v118, v119
	v_add_f32_e32 v230, v230, v118
	v_add_f32_e32 v252, v252, v119
	v_exp_f32_e32 v127, v127
	s_waitcnt lgkmcnt(0)
	v_mfma_f32_32x32x16_bf16 v[0:15], v[152:155], v[156:159], v[0:15]
	ds_read_b64_tr_b16 v[156:157], v205 offset:43008
	ds_read_b64_tr_b16 v[158:159], v205 offset:43520
	ds_read_b64_tr_b16 v[160:161], v205 offset:39936
	ds_read_b64_tr_b16 v[162:163], v205 offset:40448
	s_waitcnt lgkmcnt(2)
	v_mfma_f32_32x32x16_bf16 v[16:31], v[152:155], v[156:159], v[16:31]
	v_cvt_pk_bf16_f32 v156, v120, v121
	v_add_f32_e32 v230, v230, v120
	v_add_f32_e32 v252, v252, v121
	v_cvt_pk_bf16_f32 v157, v122, v123
	v_add_f32_e32 v230, v230, v122
	v_add_f32_e32 v252, v252, v123
	v_cvt_pk_bf16_f32 v158, v124, v125
	v_add_f32_e32 v230, v230, v124
	v_add_f32_e32 v252, v252, v125
	v_cvt_pk_bf16_f32 v159, v126, v127
	v_add_f32_e32 v230, v230, v126
	v_add_f32_e32 v252, v252, v127
	ds_read_b64_tr_b16 v[152:153], v205 offset:44032
	ds_read_b64_tr_b16 v[154:155], v205 offset:44544
	s_waitcnt lgkmcnt(2)
	v_mfma_f32_32x32x16_bf16 v[0:15], v[156:159], v[160:163], v[0:15]
	s_waitcnt lgkmcnt(0)
	v_mfma_f32_32x32x16_bf16 v[16:31], v[156:159], v[152:155], v[16:31]
